# v4 plus GEMM1 ALIGN_EPI barrier moved into the leading half's epilogue; peeled-iteration vmcnt corrected from 24 to the provably safe 16
# baseline (speedup 1.0000x reference)
; #define PG8_STAGE(bufoff, gbase, voff) do { _Pragma("unroll") for (int _i = 0; _i < 2; ++_i) \
;         __builtin_amdgcn_global_load_lds((const unsigned*)((const char*)(gbase) + (voff)[_i]), (LAS unsigned*)(lds + (bufoff) + ldsw + _i * 8192), 16, 0, 0); } while (0)
; #define PG8_LDA(dst, b, h) do { _Pragma("unroll") for (int m = 0; m < 4; ++m) _Pragma("unroll") for (int k = 0; k < 2; ++k) dst[m][k] = *(const LAS bf16x8*)(lds + PG8_SA(b, h) + aoff + m * 2048 + k * 1024); } while (0)
; #define PG8_LDB(dst, b, h) do { _Pragma("unroll") for (int n = 0; n < 2; ++n) _Pragma("unroll") for (int k = 0; k < 2; ++k) dst[n][k] = *(const LAS bf16x8*)(lds + PG8_SB(b, h) + boff + n * 2048 + k * 1024); } while (0)
; #define PG8_WAIT_V(n) asm volatile("s_waitcnt vmcnt(" #n ")" ::: "memory")
; #define PG8_WAIT_L(n) asm volatile("s_waitcnt lgkmcnt(" #n ")" ::: "memory")
; #define PG8_BAR __builtin_amdgcn_s_barrier()
; #define PG8_SCHED __builtin_amdgcn_sched_barrier(0)
; template <class Epi>
; __device__ __forceinline__ void gemm_phase(LAS unsigned char* lds, const Gemm g, const StaticOrder& S, const Epi& E) {
;     ...
;         const bool has_next = S.next(ui + 1, nxt);
;         const char* nA = has_next ? (const char*)g.A + (size_t)nxt.pm * tstepA : cA; const char* nB = has_next ? (const char*)g.Bt + (size_t)nxt.pn * tstepB : cB;
;         const int nh = Epi::MID ? 2 : 1, nth = nt / nh;
;         for (int hf = 0; hf < nh; ++hf) {
;         for (int t = hf * nth; t < (hf + 1) * nth; t += 2) {
;             const bool last = (t == nt - 2);
;             const char* a1 = cA + (size_t)(t + 1) * kstep;
;             const char* a2 = last ? nA : cA + (size_t)(t + 2) * kstep; const char* b2 = last ? nB : cB + (size_t)(t + 2) * kstep;
;             const char* a3 = a2 + kstep; const char* b3 = b2 + kstep;
;             PG8_LDB(B0, 0, 0); PG8_LDB(B1, 0, 1); PG8_SCHED; PG8_LDA(At, 0, 0); PG8_STAGE(PG8_SA(1, 1), a1 + hstepA, voffA);
;             PG8_WAIT_V(8); PG8_WAIT_L(0); PG8_BAR; PG8_MMA(0, 0, At, B0); PG8_MMA(0, 1, At, B1); PG8_BAR; PG8_SCHED;
;     ...
; #pragma unroll
;         for (int a = 0; a < 2; ++a)
; #pragma unroll
;             for (int b = 0; b < 2; ++b)
; #pragma unroll
;                 for (int m = 0; m < 4; ++m)
; #pragma unroll
;                     for (int n = 0; n < 2; ++n) acc[a][b][m][n] = (f32x4){0.f, 0.f, 0.f, 0.f};
;         cur = nxt; cA = nA; cB = nB; ++ui;
.LBB0_159:
	s_ashr_i32 s79, s78, 31
	s_lshl_b64 s[16:17], s[78:79], 19
	s_add_u32 s80, s68, s16
	s_addc_u32 s81, s69, s17
	s_and_b64 s[16:17], s[4:5], exec
	s_cselect_b32 s7, s81, s9
	s_cselect_b32 s12, s80, s8
	s_ashr_i32 s77, s76, 31
	s_lshl_b64 s[16:17], s[76:77], 19
	s_add_u32 s82, s18, s16
	s_addc_u32 s83, s19, s17
	s_and_b64 s[16:17], s[4:5], exec
	s_cselect_b32 s16, s83, s87
	s_cselect_b32 s17, s82, s86
	s_add_u32 s8, s8, 0x40080
	s_addc_u32 s9, s9, 0
	s_add_u32 s77, s86, 0x100
	v_mov_b32_e32 v0, 0
	s_addc_u32 s79, s87, 0
	s_mov_b32 s88, -2
	v_mov_b32_e32 v1, v0
	v_mov_b32_e32 v2, v0
	v_mov_b32_e32 v3, v0
	v_mov_b32_e32 v8, v0
	v_mov_b32_e32 v9, v0
	v_mov_b32_e32 v10, v0
	v_mov_b32_e32 v11, v0
	v_mov_b32_e32 v16, v0
	v_mov_b32_e32 v17, v0
	v_mov_b32_e32 v18, v0
	v_mov_b32_e32 v19, v0
	v_mov_b32_e32 v24, v0
	v_mov_b32_e32 v25, v0
	v_mov_b32_e32 v26, v0
	v_mov_b32_e32 v27, v0
	v_mov_b32_e32 v32, v0
	v_mov_b32_e32 v33, v0
	v_mov_b32_e32 v34, v0
	v_mov_b32_e32 v35, v0
	v_mov_b32_e32 v40, v0
	v_mov_b32_e32 v41, v0
	v_mov_b32_e32 v42, v0
	v_mov_b32_e32 v43, v0
	v_mov_b32_e32 v48, v0
	v_mov_b32_e32 v49, v0
	v_mov_b32_e32 v50, v0
	v_mov_b32_e32 v51, v0
	v_mov_b32_e32 v56, v0
	v_mov_b32_e32 v57, v0
	v_mov_b32_e32 v58, v0
	v_mov_b32_e32 v59, v0
	v_mov_b32_e32 v4, v0
	v_mov_b32_e32 v5, v0
	v_mov_b32_e32 v6, v0
	v_mov_b32_e32 v7, v0
	v_mov_b32_e32 v12, v0
	v_mov_b32_e32 v13, v0
	v_mov_b32_e32 v14, v0
	v_mov_b32_e32 v15, v0
	v_mov_b32_e32 v20, v0
	v_mov_b32_e32 v21, v0
	v_mov_b32_e32 v22, v0
	v_mov_b32_e32 v23, v0
	v_mov_b32_e32 v28, v0
	v_mov_b32_e32 v29, v0
	v_mov_b32_e32 v30, v0
	v_mov_b32_e32 v31, v0
	v_mov_b32_e32 v36, v0
	v_mov_b32_e32 v37, v0
	v_mov_b32_e32 v38, v0
	v_mov_b32_e32 v39, v0
	v_mov_b32_e32 v44, v0
	v_mov_b32_e32 v45, v0
	v_mov_b32_e32 v46, v0
	v_mov_b32_e32 v47, v0
	v_mov_b32_e32 v52, v0
	v_mov_b32_e32 v53, v0
	v_mov_b32_e32 v54, v0
	v_mov_b32_e32 v55, v0
	v_mov_b32_e32 v60, v0
	v_mov_b32_e32 v61, v0
	v_mov_b32_e32 v62, v0
	v_mov_b32_e32 v63, v0
	v_mov_b32_e32 v64, v0
	v_mov_b32_e32 v65, v0
	v_mov_b32_e32 v66, v0
	v_mov_b32_e32 v67, v0
	v_mov_b32_e32 v72, v0
	v_mov_b32_e32 v73, v0
	v_mov_b32_e32 v74, v0
	v_mov_b32_e32 v75, v0
	v_mov_b32_e32 v80, v0
	v_mov_b32_e32 v81, v0
	v_mov_b32_e32 v82, v0
	v_mov_b32_e32 v83, v0
	v_mov_b32_e32 v88, v0
	v_mov_b32_e32 v89, v0
	v_mov_b32_e32 v90, v0
	v_mov_b32_e32 v91, v0
	v_mov_b32_e32 v96, v0
	v_mov_b32_e32 v97, v0
	v_mov_b32_e32 v98, v0
	v_mov_b32_e32 v99, v0
	v_mov_b32_e32 v104, v0
	v_mov_b32_e32 v105, v0
	v_mov_b32_e32 v106, v0
	v_mov_b32_e32 v107, v0
	v_mov_b32_e32 v112, v0
	v_mov_b32_e32 v113, v0
	v_mov_b32_e32 v114, v0
	v_mov_b32_e32 v115, v0
	v_mov_b32_e32 v120, v0
	v_mov_b32_e32 v121, v0
	v_mov_b32_e32 v122, v0
	v_mov_b32_e32 v123, v0
	v_mov_b32_e32 v68, v0
	v_mov_b32_e32 v69, v0
	v_mov_b32_e32 v70, v0
	v_mov_b32_e32 v71, v0
	v_mov_b32_e32 v76, v0
	v_mov_b32_e32 v77, v0
	v_mov_b32_e32 v78, v0
	v_mov_b32_e32 v79, v0
	v_mov_b32_e32 v84, v0
	v_mov_b32_e32 v85, v0
	v_mov_b32_e32 v86, v0
	v_mov_b32_e32 v87, v0
	v_mov_b32_e32 v92, v0
	v_mov_b32_e32 v93, v0
	v_mov_b32_e32 v94, v0
	v_mov_b32_e32 v95, v0
	v_mov_b32_e32 v100, v0
	v_mov_b32_e32 v101, v0
	v_mov_b32_e32 v102, v0
	v_mov_b32_e32 v103, v0
	v_mov_b32_e32 v108, v0
	v_mov_b32_e32 v109, v0
	v_mov_b32_e32 v110, v0
	v_mov_b32_e32 v111, v0
	v_mov_b32_e32 v116, v0
	v_mov_b32_e32 v117, v0
	v_mov_b32_e32 v118, v0
	v_mov_b32_e32 v119, v0
	v_mov_b32_e32 v124, v0
	v_mov_b32_e32 v125, v0
	v_mov_b32_e32 v126, v0
	v_mov_b32_e32 v127, v0
	s_cmp_eq_u32 s21, 1
	s_cbranch_scc1 .LBB0_160
	ds_read_b128 v[146:149], v164
	ds_read_b128 v[150:153], v164 offset:1024
	ds_read_b128 v[154:157], v164 offset:2048
	ds_read_b128 v[158:161], v164 offset:3072
	ds_read_b128 v[168:171], v165
	ds_read_b128 v[172:175], v165 offset:1024
	ds_read_b128 v[176:179], v165 offset:2048
	ds_read_b128 v[180:183], v165 offset:3072
	s_add_u32 s42, s8, 0xfffc0080
	s_addc_u32 s43, s9, -1
	s_cmp_eq_u32 s88, 12
	s_cselect_b32 s43, s7, s43
	s_cselect_b32 s42, s12, s42
	s_cselect_b32 s87, s16, s79
	s_cselect_b32 s86, s17, s77
	v_lshl_add_u64 v[192:193], s[8:9], 0, v[138:139]
	s_add_i32 m0, s27, 0xc000
	ds_read_b128 v[184:187], v166
	ds_read_b128 v[188:191], v166 offset:1024
	ds_read_b128 v[196:199], v166 offset:2048
	ds_read_b128 v[200:203], v166 offset:3072
	ds_read_b128 v[204:207], v166 offset:4096
	ds_read_b128 v[208:211], v166 offset:5120
	ds_read_b128 v[212:215], v166 offset:6144
	ds_read_b128 v[216:219], v166 offset:7168
	global_load_lds_dwordx4 v[192:193], off
	v_lshl_add_u64 v[192:193], s[8:9], 0, v[140:141]
	s_add_i32 m0, s27, 0xe000
	s_nop 0
	global_load_lds_dwordx4 v[192:193], off
	s_waitcnt vmcnt(16)
	s_waitcnt lgkmcnt(0)
	s_barrier
; #define PG8_STAGE(bufoff, gbase, voff) do { _Pragma("unroll") for (int _i = 0; _i < 2; ++_i) \
;         __builtin_amdgcn_global_load_lds((const unsigned*)((const char*)(gbase) + (voff)[_i]), (LAS unsigned*)(lds + (bufoff) + ldsw + _i * 8192), 16, 0, 0); } while (0)
; #define PG8_LDA(dst, b, h) do { _Pragma("unroll") for (int m = 0; m < 4; ++m) _Pragma("unroll") for (int k = 0; k < 2; ++k) dst[m][k] = *(const LAS bf16x8*)(lds + PG8_SA(b, h) + aoff + m * 2048 + k * 1024); } while (0)
; #define PG8_LDB(dst, b, h) do { _Pragma("unroll") for (int n = 0; n < 2; ++n) _Pragma("unroll") for (int k = 0; k < 2; ++k) dst[n][k] = *(const LAS bf16x8*)(lds + PG8_SB(b, h) + boff + n * 2048 + k * 1024); } while (0)
; #define PG8_MMA(ai, bj, At, Bt) do { __builtin_amdgcn_s_setprio(1); _Pragma("unroll") for (int m = 0; m < 4; ++m) _Pragma("unroll") for (int n = 0; n < 2; ++n) _Pragma("unroll") for (int k = 0; k < 2; ++k) \
;         acc[ai][bj][m][n] = __builtin_amdgcn_mfma_f32_16x16x32_bf16(Bt[n][k], At[m][k], acc[ai][bj][m][n], 0, 0, 0); __builtin_amdgcn_s_setprio(0); } while (0)
; #define PG8_WAIT_V(n) asm volatile("s_waitcnt vmcnt(" #n ")" ::: "memory")
; #define PG8_WAIT_L(n) asm volatile("s_waitcnt lgkmcnt(" #n ")" ::: "memory")
; #define PG8_BAR __builtin_amdgcn_s_barrier()
; #define PG8_SCHED __builtin_amdgcn_sched_barrier(0)
; template <class Epi>
; __device__ __forceinline__ void gemm_phase(LAS unsigned char* lds, const Gemm g, const StaticOrder& S, const Epi& E) {
;     ...
;             PG8_LDB(B0, 0, 0); PG8_LDB(B1, 0, 1); PG8_SCHED; PG8_LDA(At, 0, 0); PG8_STAGE(PG8_SA(1, 1), a1 + hstepA, voffA);
;             PG8_WAIT_V(8); PG8_WAIT_L(0); PG8_BAR; PG8_MMA(0, 0, At, B0); PG8_MMA(0, 1, At, B1); PG8_BAR; PG8_SCHED;
;             PG8_LDA(At, 0, 1); PG8_STAGE(PG8_SB(0, 0), b2, voffB); PG8_STAGE(PG8_SB(0, 1), b2 + hstepB, voffB); PG8_STAGE(PG8_SA(0, 0), a2, voffA);
;             PG8_WAIT_V(8); PG8_WAIT_L(0); PG8_BAR; PG8_MMA(1, 0, At, B0); PG8_MMA(1, 1, At, B1); PG8_BAR; PG8_SCHED;
;             PG8_LDB(B0, 1, 0); PG8_LDB(B1, 1, 1); PG8_SCHED; PG8_LDA(At, 1, 0); PG8_STAGE(PG8_SA(0, 1), a2 + hstepA, voffA);
;             PG8_WAIT_V(8); PG8_WAIT_L(0); PG8_BAR; PG8_MMA(0, 0, At, B0); PG8_MMA(0, 1, At, B1); PG8_BAR; PG8_SCHED;
	s_setprio 1
	s_waitcnt lgkmcnt(0)
	v_mfma_f32_16x16x32_bf16 v[124:127], v[146:149], v[184:187], v[124:127]
	v_mfma_f32_16x16x32_bf16 v[116:119], v[154:157], v[184:187], v[116:119]
	v_mfma_f32_16x16x32_bf16 v[108:111], v[146:149], v[196:199], v[108:111]
	v_mfma_f32_16x16x32_bf16 v[100:103], v[154:157], v[196:199], v[100:103]
	v_mfma_f32_16x16x32_bf16 v[92:95], v[146:149], v[204:207], v[92:95]
	v_mfma_f32_16x16x32_bf16 v[84:87], v[154:157], v[204:207], v[84:87]
	v_mfma_f32_16x16x32_bf16 v[76:79], v[146:149], v[212:215], v[76:79]
	v_mfma_f32_16x16x32_bf16 v[68:71], v[154:157], v[212:215], v[68:71]
	v_mfma_f32_16x16x32_bf16 v[124:127], v[150:153], v[188:191], v[124:127]
	v_mfma_f32_16x16x32_bf16 v[116:119], v[158:161], v[188:191], v[116:119]
	v_mfma_f32_16x16x32_bf16 v[108:111], v[150:153], v[200:203], v[108:111]
	v_mfma_f32_16x16x32_bf16 v[100:103], v[158:161], v[200:203], v[100:103]
	v_mfma_f32_16x16x32_bf16 v[92:95], v[150:153], v[208:211], v[92:95]
	v_mfma_f32_16x16x32_bf16 v[84:87], v[158:161], v[208:211], v[84:87]
	v_mfma_f32_16x16x32_bf16 v[76:79], v[150:153], v[216:219], v[76:79]
	v_mfma_f32_16x16x32_bf16 v[68:71], v[158:161], v[216:219], v[68:71]
	s_setprio 0
	s_setprio 1
	v_mfma_f32_16x16x32_bf16 v[120:123], v[168:171], v[184:187], v[120:123]
	v_mfma_f32_16x16x32_bf16 v[112:115], v[176:179], v[184:187], v[112:115]
	v_mfma_f32_16x16x32_bf16 v[104:107], v[168:171], v[196:199], v[104:107]
	v_mfma_f32_16x16x32_bf16 v[96:99], v[176:179], v[196:199], v[96:99]
	v_mfma_f32_16x16x32_bf16 v[88:91], v[168:171], v[204:207], v[88:91]
	v_mfma_f32_16x16x32_bf16 v[80:83], v[176:179], v[204:207], v[80:83]
	v_mfma_f32_16x16x32_bf16 v[72:75], v[168:171], v[212:215], v[72:75]
	v_mfma_f32_16x16x32_bf16 v[64:67], v[176:179], v[212:215], v[64:67]
	v_mfma_f32_16x16x32_bf16 v[120:123], v[172:175], v[188:191], v[120:123]
	v_mfma_f32_16x16x32_bf16 v[112:115], v[180:183], v[188:191], v[112:115]
	v_mfma_f32_16x16x32_bf16 v[104:107], v[172:175], v[200:203], v[104:107]
	v_mfma_f32_16x16x32_bf16 v[96:99], v[180:183], v[200:203], v[96:99]
	v_mfma_f32_16x16x32_bf16 v[88:91], v[172:175], v[208:211], v[88:91]
	v_mfma_f32_16x16x32_bf16 v[80:83], v[180:183], v[208:211], v[80:83]
	v_mfma_f32_16x16x32_bf16 v[72:75], v[172:175], v[216:219], v[72:75]
	v_mfma_f32_16x16x32_bf16 v[64:67], v[180:183], v[216:219], v[64:67]
	s_setprio 0
	s_barrier
	s_add_i32 s89, s1, s3
	v_lshl_add_u64 v[192:193], s[86:87], 0, v[130:131]
	s_mov_b32 m0, s89
	ds_read_b128 v[184:187], v166 offset:16384
	ds_read_b128 v[188:191], v166 offset:17408
	ds_read_b128 v[196:199], v166 offset:18432
	ds_read_b128 v[200:203], v166 offset:19456
	ds_read_b128 v[204:207], v166 offset:20480
	ds_read_b128 v[208:211], v166 offset:21504
	ds_read_b128 v[212:215], v166 offset:22528
	ds_read_b128 v[216:219], v166 offset:23552
	global_load_lds_dwordx4 v[192:193], off
	s_add_i32 m0, s89, 0x2000
	s_add_u32 s90, s86, 0x40000
	v_lshl_add_u64 v[220:221], s[86:87], 0, v[134:135]
	s_addc_u32 s91, s87, 0
	s_add_i32 s89, s20, s3
	global_load_lds_dwordx4 v[220:221], off
	v_lshl_add_u64 v[222:223], s[90:91], 0, v[130:131]
	s_mov_b32 m0, s89
	v_lshl_add_u64 v[224:225], s[42:43], 0, v[132:133]
	global_load_lds_dwordx4 v[222:223], off
	v_lshl_add_u64 v[222:223], s[90:91], 0, v[134:135]
	s_add_i32 m0, s89, 0x2000
	s_nop 0
	global_load_lds_dwordx4 v[222:223], off
	v_lshl_add_u64 v[222:223], s[42:43], 0, v[128:129]
	s_mov_b32 m0, s27
	s_nop 0
	global_load_lds_dwordx4 v[222:223], off
	s_mov_b32 m0, s29
	s_nop 0
	global_load_lds_dwordx4 v[224:225], off
	s_waitcnt vmcnt(16)
	s_waitcnt lgkmcnt(0)
	s_barrier
	s_setprio 1
	s_waitcnt lgkmcnt(0)
	v_mfma_f32_16x16x32_bf16 v[60:63], v[146:149], v[184:187], v[60:63]
	v_mfma_f32_16x16x32_bf16 v[52:55], v[154:157], v[184:187], v[52:55]
	v_mfma_f32_16x16x32_bf16 v[44:47], v[146:149], v[196:199], v[44:47]
	v_mfma_f32_16x16x32_bf16 v[36:39], v[154:157], v[196:199], v[36:39]
	v_mfma_f32_16x16x32_bf16 v[28:31], v[146:149], v[204:207], v[28:31]
	v_mfma_f32_16x16x32_bf16 v[20:23], v[154:157], v[204:207], v[20:23]
	v_mfma_f32_16x16x32_bf16 v[12:15], v[146:149], v[212:215], v[12:15]
	v_mfma_f32_16x16x32_bf16 v[4:7], v[154:157], v[212:215], v[4:7]
	v_mfma_f32_16x16x32_bf16 v[60:63], v[150:153], v[188:191], v[60:63]
	v_mfma_f32_16x16x32_bf16 v[52:55], v[158:161], v[188:191], v[52:55]
	v_mfma_f32_16x16x32_bf16 v[44:47], v[150:153], v[200:203], v[44:47]
	v_mfma_f32_16x16x32_bf16 v[36:39], v[158:161], v[200:203], v[36:39]
	v_mfma_f32_16x16x32_bf16 v[28:31], v[150:153], v[208:211], v[28:31]
	v_mfma_f32_16x16x32_bf16 v[20:23], v[158:161], v[208:211], v[20:23]
	v_mfma_f32_16x16x32_bf16 v[12:15], v[150:153], v[216:219], v[12:15]
	v_mfma_f32_16x16x32_bf16 v[4:7], v[158:161], v[216:219], v[4:7]
	s_setprio 0
	s_setprio 1
	v_mfma_f32_16x16x32_bf16 v[56:59], v[168:171], v[184:187], v[56:59]
	v_mfma_f32_16x16x32_bf16 v[48:51], v[176:179], v[184:187], v[48:51]
	v_mfma_f32_16x16x32_bf16 v[40:43], v[168:171], v[196:199], v[40:43]
	v_mfma_f32_16x16x32_bf16 v[32:35], v[176:179], v[196:199], v[32:35]
	v_mfma_f32_16x16x32_bf16 v[24:27], v[168:171], v[204:207], v[24:27]
	v_mfma_f32_16x16x32_bf16 v[16:19], v[176:179], v[204:207], v[16:19]
	v_mfma_f32_16x16x32_bf16 v[8:11], v[168:171], v[212:215], v[8:11]
	v_mfma_f32_16x16x32_bf16 v[0:3], v[176:179], v[212:215], v[0:3]
	v_mfma_f32_16x16x32_bf16 v[56:59], v[172:175], v[188:191], v[56:59]
	v_mfma_f32_16x16x32_bf16 v[48:51], v[180:183], v[188:191], v[48:51]
	v_mfma_f32_16x16x32_bf16 v[40:43], v[172:175], v[200:203], v[40:43]
	v_mfma_f32_16x16x32_bf16 v[32:35], v[180:183], v[200:203], v[32:35]
	v_mfma_f32_16x16x32_bf16 v[24:27], v[172:175], v[208:211], v[24:27]
	v_mfma_f32_16x16x32_bf16 v[16:19], v[180:183], v[208:211], v[16:19]
	v_mfma_f32_16x16x32_bf16 v[8:11], v[172:175], v[216:219], v[8:11]
	v_mfma_f32_16x16x32_bf16 v[0:3], v[180:183], v[216:219], v[0:3]
	s_setprio 0
	s_barrier
; #define PG8_STAGE(bufoff, gbase, voff) do { _Pragma("unroll") for (int _i = 0; _i < 2; ++_i) \
;         __builtin_amdgcn_global_load_lds((const unsigned*)((const char*)(gbase) + (voff)[_i]), (LAS unsigned*)(lds + (bufoff) + ldsw + _i * 8192), 16, 0, 0); } while (0)
; #define PG8_LDA(dst, b, h) do { _Pragma("unroll") for (int m = 0; m < 4; ++m) _Pragma("unroll") for (int k = 0; k < 2; ++k) dst[m][k] = *(const LAS bf16x8*)(lds + PG8_SA(b, h) + aoff + m * 2048 + k * 1024); } while (0)
; #define PG8_LDB(dst, b, h) do { _Pragma("unroll") for (int n = 0; n < 2; ++n) _Pragma("unroll") for (int k = 0; k < 2; ++k) dst[n][k] = *(const LAS bf16x8*)(lds + PG8_SB(b, h) + boff + n * 2048 + k * 1024); } while (0)
; #define PG8_MMA(ai, bj, At, Bt) do { __builtin_amdgcn_s_setprio(1); _Pragma("unroll") for (int m = 0; m < 4; ++m) _Pragma("unroll") for (int n = 0; n < 2; ++n) _Pragma("unroll") for (int k = 0; k < 2; ++k) \
;         acc[ai][bj][m][n] = __builtin_amdgcn_mfma_f32_16x16x32_bf16(Bt[n][k], At[m][k], acc[ai][bj][m][n], 0, 0, 0); __builtin_amdgcn_s_setprio(0); } while (0)
; #define PG8_WAIT_V(n) asm volatile("s_waitcnt vmcnt(" #n ")" ::: "memory")
; #define PG8_WAIT_L(n) asm volatile("s_waitcnt lgkmcnt(" #n ")" ::: "memory")
; #define PG8_BAR __builtin_amdgcn_s_barrier()
; #define PG8_SCHED __builtin_amdgcn_sched_barrier(0)
; template <class Epi>
; __device__ __forceinline__ void gemm_phase(LAS unsigned char* lds, const Gemm g, const StaticOrder& S, const Epi& E) {
;     ...
;             PG8_LDB(B0, 1, 0); PG8_LDB(B1, 1, 1); PG8_SCHED; PG8_LDA(At, 1, 0); PG8_STAGE(PG8_SA(0, 1), a2 + hstepA, voffA);
;             PG8_WAIT_V(8); PG8_WAIT_L(0); PG8_BAR; PG8_MMA(0, 0, At, B0); PG8_MMA(0, 1, At, B1); PG8_BAR; PG8_SCHED;
;             PG8_LDA(At, 1, 1); PG8_STAGE(PG8_SB(1, 0), b3, voffB); PG8_STAGE(PG8_SB(1, 1), b3 + hstepB, voffB); PG8_STAGE(PG8_SA(1, 0), a3, voffA);
;             PG8_WAIT_V(8); PG8_WAIT_L(0); PG8_BAR; PG8_MMA(1, 0, At, B0); PG8_MMA(1, 1, At, B1); PG8_BAR; PG8_SCHED;
	s_add_i32 s89, 0, 0x18000
	s_add_i32 s90, 0, 0x1c000
	v_add_u32_e32 v158, s89, v163
	v_add_u32_e32 v167, s90, v163
	ds_read_b128 v[146:149], v158
	ds_read_b128 v[150:153], v158 offset:1024
	ds_read_b128 v[154:157], v158 offset:2048
	ds_read_b128 v[158:161], v158 offset:3072
	ds_read_b128 v[168:171], v167
	ds_read_b128 v[172:175], v167 offset:1024
	ds_read_b128 v[176:179], v167 offset:2048
	ds_read_b128 v[180:183], v167 offset:3072
	s_add_u32 s42, s42, 0x40000
	s_addc_u32 s43, s43, 0
	s_mov_b32 m0, s31
	v_lshl_add_u64 v[226:227], s[42:43], 0, v[128:129]
	ds_read_b128 v[184:187], v166 offset:32768
	ds_read_b128 v[188:191], v166 offset:33792
	ds_read_b128 v[196:199], v166 offset:34816
	ds_read_b128 v[200:203], v166 offset:35840
	ds_read_b128 v[204:207], v166 offset:36864
	ds_read_b128 v[208:211], v166 offset:37888
	ds_read_b128 v[212:215], v166 offset:38912
	ds_read_b128 v[216:219], v166 offset:39936
	global_load_lds_dwordx4 v[226:227], off
	v_lshl_add_u64 v[226:227], s[42:43], 0, v[132:133]
	s_mov_b32 m0, s35
	s_nop 0
	global_load_lds_dwordx4 v[226:227], off
	s_waitcnt vmcnt(8)
	s_waitcnt lgkmcnt(0)
	s_barrier
	s_setprio 1
	s_waitcnt lgkmcnt(0)
	v_mfma_f32_16x16x32_bf16 v[124:127], v[146:149], v[184:187], v[124:127]
	v_mfma_f32_16x16x32_bf16 v[116:119], v[154:157], v[184:187], v[116:119]
	v_mfma_f32_16x16x32_bf16 v[108:111], v[146:149], v[196:199], v[108:111]
	v_mfma_f32_16x16x32_bf16 v[100:103], v[154:157], v[196:199], v[100:103]
	v_mfma_f32_16x16x32_bf16 v[92:95], v[146:149], v[204:207], v[92:95]
	v_mfma_f32_16x16x32_bf16 v[84:87], v[154:157], v[204:207], v[84:87]
	v_mfma_f32_16x16x32_bf16 v[76:79], v[146:149], v[212:215], v[76:79]
	v_mfma_f32_16x16x32_bf16 v[68:71], v[154:157], v[212:215], v[68:71]
	v_mfma_f32_16x16x32_bf16 v[124:127], v[150:153], v[188:191], v[124:127]
	v_mfma_f32_16x16x32_bf16 v[116:119], v[158:161], v[188:191], v[116:119]
	v_mfma_f32_16x16x32_bf16 v[108:111], v[150:153], v[200:203], v[108:111]
	v_mfma_f32_16x16x32_bf16 v[100:103], v[158:161], v[200:203], v[100:103]
	v_mfma_f32_16x16x32_bf16 v[92:95], v[150:153], v[208:211], v[92:95]
	v_mfma_f32_16x16x32_bf16 v[84:87], v[158:161], v[208:211], v[84:87]
	v_mfma_f32_16x16x32_bf16 v[76:79], v[150:153], v[216:219], v[76:79]
	v_mfma_f32_16x16x32_bf16 v[68:71], v[158:161], v[216:219], v[68:71]
	s_setprio 0
	s_setprio 1
	v_mfma_f32_16x16x32_bf16 v[120:123], v[168:171], v[184:187], v[120:123]
	v_mfma_f32_16x16x32_bf16 v[112:115], v[176:179], v[184:187], v[112:115]
	v_mfma_f32_16x16x32_bf16 v[104:107], v[168:171], v[196:199], v[104:107]
	v_mfma_f32_16x16x32_bf16 v[96:99], v[176:179], v[196:199], v[96:99]
	v_mfma_f32_16x16x32_bf16 v[88:91], v[168:171], v[204:207], v[88:91]
	v_mfma_f32_16x16x32_bf16 v[80:83], v[176:179], v[204:207], v[80:83]
	v_mfma_f32_16x16x32_bf16 v[72:75], v[168:171], v[212:215], v[72:75]
	v_mfma_f32_16x16x32_bf16 v[64:67], v[176:179], v[212:215], v[64:67]
	v_mfma_f32_16x16x32_bf16 v[120:123], v[172:175], v[188:191], v[120:123]
	v_mfma_f32_16x16x32_bf16 v[112:115], v[180:183], v[188:191], v[112:115]
	v_mfma_f32_16x16x32_bf16 v[104:107], v[172:175], v[200:203], v[104:107]
	v_mfma_f32_16x16x32_bf16 v[96:99], v[180:183], v[200:203], v[96:99]
	v_mfma_f32_16x16x32_bf16 v[88:91], v[172:175], v[208:211], v[88:91]
	v_mfma_f32_16x16x32_bf16 v[80:83], v[180:183], v[208:211], v[80:83]
	v_mfma_f32_16x16x32_bf16 v[72:75], v[172:175], v[216:219], v[72:75]
	v_mfma_f32_16x16x32_bf16 v[64:67], v[180:183], v[216:219], v[64:67]
	s_setprio 0
	s_barrier
; #define PG8_STAGE(bufoff, gbase, voff) do { _Pragma("unroll") for (int _i = 0; _i < 2; ++_i) \
;         __builtin_amdgcn_global_load_lds((const unsigned*)((const char*)(gbase) + (voff)[_i]), (LAS unsigned*)(lds + (bufoff) + ldsw + _i * 8192), 16, 0, 0); } while (0)
; #define PG8_LDA(dst, b, h) do { _Pragma("unroll") for (int m = 0; m < 4; ++m) _Pragma("unroll") for (int k = 0; k < 2; ++k) dst[m][k] = *(const LAS bf16x8*)(lds + PG8_SA(b, h) + aoff + m * 2048 + k * 1024); } while (0)
; #define PG8_MMA(ai, bj, At, Bt) do { __builtin_amdgcn_s_setprio(1); _Pragma("unroll") for (int m = 0; m < 4; ++m) _Pragma("unroll") for (int n = 0; n < 2; ++n) _Pragma("unroll") for (int k = 0; k < 2; ++k) \
;         acc[ai][bj][m][n] = __builtin_amdgcn_mfma_f32_16x16x32_bf16(Bt[n][k], At[m][k], acc[ai][bj][m][n], 0, 0, 0); __builtin_amdgcn_s_setprio(0); } while (0)
; #define PG8_WAIT_V(n) asm volatile("s_waitcnt vmcnt(" #n ")" ::: "memory")
; #define PG8_WAIT_L(n) asm volatile("s_waitcnt lgkmcnt(" #n ")" ::: "memory")
; #define PG8_BAR __builtin_amdgcn_s_barrier()
; #define PG8_SCHED __builtin_amdgcn_sched_barrier(0)
; template <class Epi>
; __device__ __forceinline__ void gemm_phase(LAS unsigned char* lds, const Gemm g, const StaticOrder& S, const Epi& E) {
;     ...
;             PG8_LDA(At, 1, 1); PG8_STAGE(PG8_SB(1, 0), b3, voffB); PG8_STAGE(PG8_SB(1, 1), b3 + hstepB, voffB); PG8_STAGE(PG8_SA(1, 0), a3, voffA);
;             PG8_WAIT_V(8); PG8_WAIT_L(0); PG8_BAR; PG8_MMA(1, 0, At, B0); PG8_MMA(1, 1, At, B1); PG8_BAR; PG8_SCHED;
	s_add_i32 s42, s89, s3
	v_lshl_add_u64 v[192:193], v[192:193], 0, s[22:23]
	s_mov_b32 m0, s42
	ds_read_b128 v[184:187], v166 offset:49152
	ds_read_b128 v[188:191], v166 offset:50176
	ds_read_b128 v[196:199], v166 offset:51200
	ds_read_b128 v[200:203], v166 offset:52224
	ds_read_b128 v[204:207], v166 offset:53248
	ds_read_b128 v[208:211], v166 offset:54272
	ds_read_b128 v[212:215], v166 offset:55296
	ds_read_b128 v[216:219], v166 offset:56320
	global_load_lds_dwordx4 v[192:193], off
	s_add_i32 m0, s42, 0x2000
	s_add_u32 s42, s86, 0x40080
	v_lshl_add_u64 v[192:193], v[220:221], 0, s[22:23]
	s_addc_u32 s43, s87, 0
	s_add_i32 s86, s90, s3
	global_load_lds_dwordx4 v[192:193], off
	v_lshl_add_u64 v[192:193], s[42:43], 0, v[130:131]
	s_mov_b32 m0, s86
	s_nop 0
	global_load_lds_dwordx4 v[192:193], off
	v_lshl_add_u64 v[192:193], s[42:43], 0, v[134:135]
	s_add_i32 m0, s86, 0x2000
	s_nop 0
	global_load_lds_dwordx4 v[192:193], off
	v_lshl_add_u64 v[192:193], v[222:223], 0, s[22:23]
	s_mov_b32 m0, s37
	s_nop 0
	global_load_lds_dwordx4 v[192:193], off
	v_lshl_add_u64 v[192:193], v[224:225], 0, s[22:23]
	s_mov_b32 m0, s51
	s_nop 0
	global_load_lds_dwordx4 v[192:193], off
	s_waitcnt vmcnt(8)
	s_waitcnt lgkmcnt(0)
	s_barrier
	s_setprio 1
	s_waitcnt lgkmcnt(0)
	v_mfma_f32_16x16x32_bf16 v[60:63], v[146:149], v[184:187], v[60:63]
	v_mfma_f32_16x16x32_bf16 v[52:55], v[154:157], v[184:187], v[52:55]
	v_mfma_f32_16x16x32_bf16 v[44:47], v[146:149], v[196:199], v[44:47]
	v_mfma_f32_16x16x32_bf16 v[36:39], v[154:157], v[196:199], v[36:39]
	v_mfma_f32_16x16x32_bf16 v[28:31], v[146:149], v[204:207], v[28:31]
	v_mfma_f32_16x16x32_bf16 v[20:23], v[154:157], v[204:207], v[20:23]
	v_mfma_f32_16x16x32_bf16 v[12:15], v[146:149], v[212:215], v[12:15]
	v_mfma_f32_16x16x32_bf16 v[4:7], v[154:157], v[212:215], v[4:7]
	v_mfma_f32_16x16x32_bf16 v[60:63], v[150:153], v[188:191], v[60:63]
	v_mfma_f32_16x16x32_bf16 v[52:55], v[158:161], v[188:191], v[52:55]
	v_mfma_f32_16x16x32_bf16 v[44:47], v[150:153], v[200:203], v[44:47]
	v_mfma_f32_16x16x32_bf16 v[36:39], v[158:161], v[200:203], v[36:39]
	v_mfma_f32_16x16x32_bf16 v[28:31], v[150:153], v[208:211], v[28:31]
	v_mfma_f32_16x16x32_bf16 v[20:23], v[158:161], v[208:211], v[20:23]
	v_mfma_f32_16x16x32_bf16 v[12:15], v[150:153], v[216:219], v[12:15]
	v_mfma_f32_16x16x32_bf16 v[4:7], v[158:161], v[216:219], v[4:7]
	s_setprio 0
	s_setprio 1
	v_mfma_f32_16x16x32_bf16 v[56:59], v[168:171], v[184:187], v[56:59]
	v_mfma_f32_16x16x32_bf16 v[48:51], v[176:179], v[184:187], v[48:51]
	v_mfma_f32_16x16x32_bf16 v[40:43], v[168:171], v[196:199], v[40:43]
	v_mfma_f32_16x16x32_bf16 v[32:35], v[176:179], v[196:199], v[32:35]
	v_mfma_f32_16x16x32_bf16 v[24:27], v[168:171], v[204:207], v[24:27]
	v_mfma_f32_16x16x32_bf16 v[16:19], v[176:179], v[204:207], v[16:19]
	v_mfma_f32_16x16x32_bf16 v[8:11], v[168:171], v[212:215], v[8:11]
	v_mfma_f32_16x16x32_bf16 v[0:3], v[176:179], v[212:215], v[0:3]
	v_mfma_f32_16x16x32_bf16 v[56:59], v[172:175], v[188:191], v[56:59]
	v_mfma_f32_16x16x32_bf16 v[48:51], v[180:183], v[188:191], v[48:51]
	v_mfma_f32_16x16x32_bf16 v[40:43], v[172:175], v[200:203], v[40:43]
	v_mfma_f32_16x16x32_bf16 v[32:35], v[180:183], v[200:203], v[32:35]
	v_mfma_f32_16x16x32_bf16 v[24:27], v[172:175], v[208:211], v[24:27]
	v_mfma_f32_16x16x32_bf16 v[16:19], v[180:183], v[208:211], v[16:19]
	v_mfma_f32_16x16x32_bf16 v[8:11], v[172:175], v[216:219], v[8:11]
	v_mfma_f32_16x16x32_bf16 v[0:3], v[180:183], v[216:219], v[0:3]
	s_setprio 0
	s_barrier
	s_add_i32 s88, s88, 2
	s_add_u32 s8, s8, 0x100
	s_addc_u32 s9, s9, 0
	s_add_u32 s77, s77, 0x100
	s_addc_u32 s79, s79, 0
